# previous + final G4 epilogue second half: per-row sum-of-squares loads batched 2x8
# baseline (speedup 1.0000x reference)
;     __device__ __forceinline__ void operator()(f32x4 (&acc)[2][2][4][2], const pg8::Unit& u, int wr, int wc, int fr, int fq) const {
;     ...
;         f32x4 gg[2][2];
; #pragma unroll
;         for (int bj = 0; bj < 2; ++bj)
; #pragma unroll
;             for (int n = 0; n < 2; ++n) gg[bj][n] = *(const f32x4*)(fng + col0 + bj * 128 + n * 16);
; #pragma unroll
;         for (int ai = 0; ai < 2; ++ai)
; #pragma unroll
;             for (int m = 0; m < 4; ++m) {
;                 const int row = row0 + ai * 128 + m * 16;
;                 const f32x4 pa = *(const f32x4*)(ss + (size_t)row * 32 + 8 * fq), pb = *(const f32x4*)(ss + (size_t)row * 32 + 8 * fq + 4);
;                 float sq = ((pa[0] + pa[1]) + (pa[2] + pa[3])) + ((pb[0] + pb[1]) + (pb[2] + pb[3]));
;                 sq += __shfl_xor(sq, 16); sq += __shfl_xor(sq, 32);
;                 const float rinv = __builtin_amdgcn_rsqf(sq * (1.0f / DM) + 1e-6f);
;                 float* orow = oy + (size_t)row * DM + col0;
; #pragma unroll
;                 for (int bj = 0; bj < 2; ++bj)
; #pragma unroll
;                     for (int n = 0; n < 2; ++n) __builtin_nontemporal_store(acc[ai][bj][m][n] * rinv * gg[bj][n], (f32x4*)(orow + bj * 128 + n * 16));
;             }
.LBB0_904:
	s_or_b64 exec, exec, s[36:37]
	s_barrier
	v_lshl_add_u64 v[130:131], v[148:149], 0, v[130:131]
	v_mov_b32_e32 v254, v130
	v_mov_b32_e32 v255, v131
	global_load_dwordx4 v[216:219], v[254:255], off
	global_load_dwordx4 v[220:223], v[254:255], off offset:16
	global_load_dwordx4 v[224:227], v[254:255], off offset:2048
	global_load_dwordx4 v[228:231], v[254:255], off offset:2064
	s_mov_b64 s[98:99], 0x1000
	v_lshl_add_u64 v[252:253], v[254:255], 0, s[98:99]
	global_load_dwordx4 v[236:239], v[252:253], off
	global_load_dwordx4 v[240:243], v[252:253], off offset:16
	s_mov_b64 s[98:99], 0x1000
	v_lshl_add_u64 v[252:253], v[254:255], 0, s[98:99]
	global_load_dwordx4 v[244:247], v[252:253], off offset:2048
	global_load_dwordx4 v[248:251], v[252:253], off offset:2064
	v_readlane_b32 s64, v234, 3
	v_readlane_b32 s74, v234, 13
	v_readlane_b32 s75, v234, 14
	v_lshl_add_u64 v[166:167], v[148:149], 0, v[166:167]
	v_lshl_add_u64 v[170:171], v[148:149], 0, v[170:171]
	v_lshl_add_u64 v[128:129], v[128:129], 2, s[74:75]
	global_load_dwordx4 v[140:143], v[128:129], off
	global_load_dwordx4 v[136:139], v[128:129], off offset:64
	s_waitcnt lgkmcnt(0)
	global_load_dwordx4 v[132:135], v[128:129], off offset:512
	s_nop 0
	global_load_dwordx4 v[128:131], v[128:129], off offset:576
	v_lshl_add_u64 v[174:175], v[148:149], 0, v[174:175]
	s_andn2_b64 vcc, exec, s[34:35]
	v_readlane_b32 s65, v234, 4
	v_readlane_b32 s66, v234, 5
	v_readlane_b32 s67, v234, 6
	v_readlane_b32 s68, v234, 7
	v_readlane_b32 s69, v234, 8
	v_readlane_b32 s70, v234, 9
	v_readlane_b32 s71, v234, 10
	v_readlane_b32 s72, v234, 11
	v_readlane_b32 s73, v234, 12
	v_readlane_b32 s76, v234, 15
	v_readlane_b32 s77, v234, 16
	v_readlane_b32 s78, v234, 17
	v_readlane_b32 s79, v234, 18
	s_waitcnt vmcnt(4)
	v_mov_b32_e32 v188, v216
	v_mov_b32_e32 v189, v217
	v_mov_b32_e32 v190, v218
	v_mov_b32_e32 v191, v219
	v_mov_b32_e32 v196, v220
	v_mov_b32_e32 v197, v221
	v_mov_b32_e32 v198, v222
	v_mov_b32_e32 v199, v223
	v_mov_b32_e32 v192, v188
	v_mov_b32_e32 v193, v196
	v_mov_b32_e32 v196, v189
	v_mov_b32_e32 v188, v190
	v_mov_b32_e32 v189, v198
	v_mov_b32_e32 v198, v191
	v_pk_add_f32 v[190:191], v[192:193], v[196:197]
	v_pk_add_f32 v[188:189], v[188:189], v[198:199]
	s_nop 0
	v_pk_add_f32 v[188:189], v[190:191], v[188:189]
	s_nop 0
	v_add_f32_e32 v187, v188, v189
	ds_bpermute_b32 v188, v185, v187
	s_waitcnt lgkmcnt(0)
	v_add_f32_e32 v187, v187, v188
	ds_bpermute_b32 v188, v186, v187
	s_waitcnt lgkmcnt(0)
	v_add_f32_e32 v187, v187, v188
	v_fmamk_f32 v187, v187, 0x3a000000, v184
	v_rsq_f32_e32 v188, v187
	s_nop 0
	v_pk_mul_f32 v[192:193], v[124:125], v[188:189] op_sel_hi:[1,0]
	v_pk_mul_f32 v[190:191], v[126:127], v[188:189] op_sel_hi:[1,0]
	v_pk_mul_f32 v[196:197], v[120:121], v[188:189] op_sel_hi:[1,0]
	v_pk_mul_f32 v[198:199], v[122:123], v[188:189] op_sel_hi:[1,0]
	v_pk_mul_f32 v[200:201], v[92:93], v[188:189] op_sel_hi:[1,0]
	v_pk_mul_f32 v[202:203], v[94:95], v[188:189] op_sel_hi:[1,0]
	v_pk_mul_f32 v[204:205], v[88:89], v[188:189] op_sel_hi:[1,0]
	v_pk_mul_f32 v[206:207], v[90:91], v[188:189] op_sel_hi:[1,0]
	s_waitcnt vmcnt(3)
	v_pk_mul_f32 v[190:191], v[142:143], v[190:191]
	v_pk_mul_f32 v[188:189], v[140:141], v[192:193]
	s_waitcnt vmcnt(2)
	v_pk_mul_f32 v[198:199], v[138:139], v[198:199]
	v_pk_mul_f32 v[196:197], v[136:137], v[196:197]
	s_waitcnt vmcnt(1)
	v_pk_mul_f32 v[202:203], v[134:135], v[202:203]
	v_pk_mul_f32 v[200:201], v[132:133], v[200:201]
	s_waitcnt vmcnt(0)
	v_pk_mul_f32 v[206:207], v[130:131], v[206:207]
	v_pk_mul_f32 v[204:205], v[128:129], v[204:205]
	global_store_dwordx4 v[150:151], v[188:191], off nt
	global_store_dwordx4 v[150:151], v[196:199], off offset:64 nt
	global_store_dwordx4 v[150:151], v[200:203], off offset:512 nt
	global_store_dwordx4 v[150:151], v[204:207], off offset:576 nt
	v_mov_b32_e32 v188, v224
	v_mov_b32_e32 v189, v225
	v_mov_b32_e32 v190, v226
	v_mov_b32_e32 v191, v227
	s_nop 0
	v_mov_b32_e32 v196, v228
	v_mov_b32_e32 v197, v229
	v_mov_b32_e32 v198, v230
	v_mov_b32_e32 v199, v231
	v_lshl_add_u64 v[192:193], v[148:149], 0, v[168:169]
	v_mov_b32_e32 v150, v188
	v_mov_b32_e32 v151, v196
	v_mov_b32_e32 v196, v189
	v_mov_b32_e32 v166, v190
	v_mov_b32_e32 v167, v198
	v_mov_b32_e32 v198, v191
	v_pk_add_f32 v[150:151], v[150:151], v[196:197]
	v_pk_add_f32 v[166:167], v[166:167], v[198:199]
	s_nop 0
	v_pk_add_f32 v[150:151], v[150:151], v[166:167]
	s_nop 0
	v_add_f32_e32 v150, v150, v151
	ds_bpermute_b32 v151, v185, v150
	s_waitcnt lgkmcnt(0)
	v_add_f32_e32 v150, v150, v151
	ds_bpermute_b32 v151, v186, v150
	s_waitcnt lgkmcnt(0)
	v_add_f32_e32 v150, v150, v151
	v_fmamk_f32 v150, v150, 0x3a000000, v184
	v_rsq_f32_e32 v150, v150
	s_nop 0
	v_pk_mul_f32 v[166:167], v[116:117], v[150:151] op_sel_hi:[1,0]
	v_pk_mul_f32 v[168:169], v[118:119], v[150:151] op_sel_hi:[1,0]
	v_pk_mul_f32 v[188:189], v[112:113], v[150:151] op_sel_hi:[1,0]
	v_pk_mul_f32 v[190:191], v[114:115], v[150:151] op_sel_hi:[1,0]
	v_pk_mul_f32 v[196:197], v[84:85], v[150:151] op_sel_hi:[1,0]
	v_pk_mul_f32 v[198:199], v[86:87], v[150:151] op_sel_hi:[1,0]
	v_pk_mul_f32 v[200:201], v[80:81], v[150:151] op_sel_hi:[1,0]
	v_pk_mul_f32 v[150:151], v[82:83], v[150:151] op_sel_hi:[1,0]
	v_pk_mul_f32 v[168:169], v[142:143], v[168:169]
	v_pk_mul_f32 v[166:167], v[140:141], v[166:167]
	v_pk_mul_f32 v[190:191], v[138:139], v[190:191]
	v_pk_mul_f32 v[188:189], v[136:137], v[188:189]
	v_pk_mul_f32 v[198:199], v[134:135], v[198:199]
	v_pk_mul_f32 v[196:197], v[132:133], v[196:197]
	v_pk_mul_f32 v[202:203], v[130:131], v[150:151]
	v_pk_mul_f32 v[200:201], v[128:129], v[200:201]
	global_store_dwordx4 v[152:153], v[166:169], off nt
	global_store_dwordx4 v[152:153], v[188:191], off offset:64 nt
	global_store_dwordx4 v[152:153], v[196:199], off offset:512 nt
	global_store_dwordx4 v[152:153], v[200:203], off offset:576 nt
	v_mov_b32_e32 v150, v236
	v_mov_b32_e32 v151, v237
	v_mov_b32_e32 v152, v238
	v_mov_b32_e32 v153, v239
	s_nop 0
	v_mov_b32_e32 v166, v240
	v_mov_b32_e32 v167, v241
	v_mov_b32_e32 v168, v242
	v_mov_b32_e32 v169, v243
	v_mov_b32_e32 v188, v150
	v_mov_b32_e32 v189, v166
	v_mov_b32_e32 v166, v151
	v_mov_b32_e32 v150, v152
	v_mov_b32_e32 v151, v168
	v_mov_b32_e32 v168, v153
	v_pk_add_f32 v[152:153], v[188:189], v[166:167]
	v_pk_add_f32 v[150:151], v[150:151], v[168:169]
	s_nop 0
	v_pk_add_f32 v[150:151], v[152:153], v[150:151]
	s_nop 0
	v_add_f32_e32 v150, v150, v151
	ds_bpermute_b32 v151, v185, v150
	s_waitcnt lgkmcnt(0)
;     __device__ __forceinline__ void operator()(f32x4 (&acc)[2][2][4][2], const pg8::Unit& u, int wr, int wc, int fr, int fq) const {
;     ...
; #pragma unroll
;         for (int ai = 0; ai < 2; ++ai)
; #pragma unroll
;             for (int m = 0; m < 4; ++m) {
;                 const int row = row0 + ai * 128 + m * 16;
;                 const f32x4 pa = *(const f32x4*)(ss + (size_t)row * 32 + 8 * fq), pb = *(const f32x4*)(ss + (size_t)row * 32 + 8 * fq + 4);
;                 float sq = ((pa[0] + pa[1]) + (pa[2] + pa[3])) + ((pb[0] + pb[1]) + (pb[2] + pb[3]));
;                 sq += __shfl_xor(sq, 16); sq += __shfl_xor(sq, 32);
;                 const float rinv = __builtin_amdgcn_rsqf(sq * (1.0f / DM) + 1e-6f);
;                 float* orow = oy + (size_t)row * DM + col0;
; #pragma unroll
;                 for (int bj = 0; bj < 2; ++bj)
; #pragma unroll
;                     for (int n = 0; n < 2; ++n) __builtin_nontemporal_store(acc[ai][bj][m][n] * rinv * gg[bj][n], (f32x4*)(orow + bj * 128 + n * 16));
;             }
	v_add_f32_e32 v150, v150, v151
	ds_bpermute_b32 v151, v186, v150
	s_waitcnt lgkmcnt(0)
	v_add_f32_e32 v150, v150, v151
	v_fmamk_f32 v150, v150, 0x3a000000, v184
	v_rsq_f32_e32 v150, v150
	s_nop 0
	v_pk_mul_f32 v[166:167], v[108:109], v[150:151] op_sel_hi:[1,0]
	v_pk_mul_f32 v[152:153], v[110:111], v[150:151] op_sel_hi:[1,0]
	v_pk_mul_f32 v[188:189], v[104:105], v[150:151] op_sel_hi:[1,0]
	v_pk_mul_f32 v[168:169], v[106:107], v[150:151] op_sel_hi:[1,0]
	v_pk_mul_f32 v[192:193], v[76:77], v[150:151] op_sel_hi:[1,0]
	v_pk_mul_f32 v[190:191], v[78:79], v[150:151] op_sel_hi:[1,0]
	v_pk_mul_f32 v[196:197], v[72:73], v[150:151] op_sel_hi:[1,0]
	v_pk_mul_f32 v[198:199], v[74:75], v[150:151] op_sel_hi:[1,0]
	v_pk_mul_f32 v[152:153], v[142:143], v[152:153]
	v_pk_mul_f32 v[150:151], v[140:141], v[166:167]
	v_pk_mul_f32 v[168:169], v[138:139], v[168:169]
	v_pk_mul_f32 v[166:167], v[136:137], v[188:189]
	v_pk_mul_f32 v[190:191], v[134:135], v[190:191]
	v_pk_mul_f32 v[188:189], v[132:133], v[192:193]
	v_pk_mul_f32 v[198:199], v[130:131], v[198:199]
	v_pk_mul_f32 v[196:197], v[128:129], v[196:197]
	global_store_dwordx4 v[154:155], v[150:153], off nt
	global_store_dwordx4 v[154:155], v[166:169], off offset:64 nt
	global_store_dwordx4 v[154:155], v[188:191], off offset:512 nt
	global_store_dwordx4 v[154:155], v[196:199], off offset:576 nt
	v_mov_b32_e32 v150, v244
	v_mov_b32_e32 v151, v245
	v_mov_b32_e32 v152, v246
	v_mov_b32_e32 v153, v247
	s_nop 0
	v_mov_b32_e32 v166, v248
	v_mov_b32_e32 v167, v249
	v_mov_b32_e32 v168, v250
	v_mov_b32_e32 v169, v251
	v_mov_b32_e32 v154, v150
	v_mov_b32_e32 v155, v166
	v_mov_b32_e32 v166, v151
	v_mov_b32_e32 v150, v152
	v_mov_b32_e32 v151, v168
	v_mov_b32_e32 v168, v153
	v_pk_add_f32 v[152:153], v[154:155], v[166:167]
	v_pk_add_f32 v[150:151], v[150:151], v[168:169]
	v_lshl_add_u64 v[154:155], v[148:149], 0, v[172:173]
	v_pk_add_f32 v[150:151], v[152:153], v[150:151]
	s_nop 0
	v_add_f32_e32 v150, v150, v151
	ds_bpermute_b32 v151, v185, v150
	s_waitcnt lgkmcnt(0)
	v_add_f32_e32 v150, v150, v151
	ds_bpermute_b32 v151, v186, v150
	s_waitcnt lgkmcnt(0)
	v_add_f32_e32 v150, v150, v151
	v_fmamk_f32 v150, v150, 0x3a000000, v184
	v_rsq_f32_e32 v150, v150
	s_nop 0
	v_pk_mul_f32 v[166:167], v[100:101], v[150:151] op_sel_hi:[1,0]
	v_pk_mul_f32 v[152:153], v[102:103], v[150:151] op_sel_hi:[1,0]
	v_pk_mul_f32 v[170:171], v[96:97], v[150:151] op_sel_hi:[1,0]
	v_pk_mul_f32 v[168:169], v[98:99], v[150:151] op_sel_hi:[1,0]
	v_pk_mul_f32 v[188:189], v[68:69], v[150:151] op_sel_hi:[1,0]
	v_pk_mul_f32 v[172:173], v[70:71], v[150:151] op_sel_hi:[1,0]
	v_pk_mul_f32 v[192:193], v[64:65], v[150:151] op_sel_hi:[1,0]
	v_pk_mul_f32 v[190:191], v[66:67], v[150:151] op_sel_hi:[1,0]
	v_pk_mul_f32 v[152:153], v[142:143], v[152:153]
	v_pk_mul_f32 v[150:151], v[140:141], v[166:167]
	v_pk_mul_f32 v[168:169], v[138:139], v[168:169]
	v_pk_mul_f32 v[166:167], v[136:137], v[170:171]
	v_pk_mul_f32 v[172:173], v[134:135], v[172:173]
	v_pk_mul_f32 v[170:171], v[132:133], v[188:189]
	v_pk_mul_f32 v[190:191], v[130:131], v[190:191]
	v_pk_mul_f32 v[188:189], v[128:129], v[192:193]
	global_store_dwordx4 v[156:157], v[150:153], off nt
	global_store_dwordx4 v[156:157], v[166:169], off offset:64 nt
	global_store_dwordx4 v[156:157], v[170:173], off offset:512 nt
	global_store_dwordx4 v[156:157], v[188:191], off offset:576 nt
	s_mov_b64 s[98:99], 0x4000
	v_lshl_add_u64 v[252:253], v[254:255], 0, s[98:99]
	global_load_dwordx4 v[216:219], v[252:253], off
	global_load_dwordx4 v[220:223], v[252:253], off offset:16
	s_mov_b64 s[98:99], 0x4000
	v_lshl_add_u64 v[252:253], v[254:255], 0, s[98:99]
	global_load_dwordx4 v[224:227], v[252:253], off offset:2048
	global_load_dwordx4 v[228:231], v[252:253], off offset:2064
	s_mov_b64 s[98:99], 0x5000
	v_lshl_add_u64 v[252:253], v[254:255], 0, s[98:99]
	global_load_dwordx4 v[236:239], v[252:253], off
	global_load_dwordx4 v[240:243], v[252:253], off offset:16
	s_mov_b64 s[98:99], 0x5000
	v_lshl_add_u64 v[252:253], v[254:255], 0, s[98:99]
	global_load_dwordx4 v[244:247], v[252:253], off offset:2048
	global_load_dwordx4 v[248:251], v[252:253], off offset:2064
	s_waitcnt vmcnt(0)
	v_mov_b32_e32 v150, v216
	v_mov_b32_e32 v151, v217
	v_mov_b32_e32 v152, v218
	v_mov_b32_e32 v153, v219
	s_nop 0
	v_mov_b32_e32 v154, v220
	v_mov_b32_e32 v155, v221
	v_mov_b32_e32 v156, v222
	v_mov_b32_e32 v157, v223
	v_mov_b32_e32 v166, v150
	v_mov_b32_e32 v167, v154
	v_mov_b32_e32 v154, v151
	v_mov_b32_e32 v150, v152
	v_mov_b32_e32 v151, v156
	v_mov_b32_e32 v156, v153
	v_pk_add_f32 v[152:153], v[166:167], v[154:155]
	v_pk_add_f32 v[150:151], v[150:151], v[156:157]
	s_nop 0
	v_pk_add_f32 v[150:151], v[152:153], v[150:151]
	s_nop 0
	v_add_f32_e32 v150, v150, v151
	ds_bpermute_b32 v151, v185, v150
	s_waitcnt lgkmcnt(0)
	v_add_f32_e32 v150, v150, v151
	ds_bpermute_b32 v151, v186, v150
	s_waitcnt lgkmcnt(0)
;     __device__ __forceinline__ void operator()(f32x4 (&acc)[2][2][4][2], const pg8::Unit& u, int wr, int wc, int fr, int fq) const {
;     ...
; #pragma unroll
;         for (int ai = 0; ai < 2; ++ai)
; #pragma unroll
;             for (int m = 0; m < 4; ++m) {
;                 const int row = row0 + ai * 128 + m * 16;
;                 const f32x4 pa = *(const f32x4*)(ss + (size_t)row * 32 + 8 * fq), pb = *(const f32x4*)(ss + (size_t)row * 32 + 8 * fq + 4);
;                 float sq = ((pa[0] + pa[1]) + (pa[2] + pa[3])) + ((pb[0] + pb[1]) + (pb[2] + pb[3]));
;                 sq += __shfl_xor(sq, 16); sq += __shfl_xor(sq, 32);
;                 const float rinv = __builtin_amdgcn_rsqf(sq * (1.0f / DM) + 1e-6f);
;                 float* orow = oy + (size_t)row * DM + col0;
; #pragma unroll
;                 for (int bj = 0; bj < 2; ++bj)
; #pragma unroll
;                     for (int n = 0; n < 2; ++n) __builtin_nontemporal_store(acc[ai][bj][m][n] * rinv * gg[bj][n], (f32x4*)(orow + bj * 128 + n * 16));
;             }
	v_add_f32_e32 v150, v150, v151
	v_fmamk_f32 v150, v150, 0x3a000000, v184
	v_rsq_f32_e32 v150, v150
	s_nop 0
	v_pk_mul_f32 v[154:155], v[60:61], v[150:151] op_sel_hi:[1,0]
	v_pk_mul_f32 v[152:153], v[62:63], v[150:151] op_sel_hi:[1,0]
	v_pk_mul_f32 v[166:167], v[56:57], v[150:151] op_sel_hi:[1,0]
	v_pk_mul_f32 v[156:157], v[58:59], v[150:151] op_sel_hi:[1,0]
	v_pk_mul_f32 v[170:171], v[28:29], v[150:151] op_sel_hi:[1,0]
	v_pk_mul_f32 v[168:169], v[30:31], v[150:151] op_sel_hi:[1,0]
	v_pk_mul_f32 v[188:189], v[24:25], v[150:151] op_sel_hi:[1,0]
	v_pk_mul_f32 v[172:173], v[26:27], v[150:151] op_sel_hi:[1,0]
	v_pk_mul_f32 v[152:153], v[142:143], v[152:153]
	v_pk_mul_f32 v[150:151], v[140:141], v[154:155]
	v_pk_mul_f32 v[156:157], v[138:139], v[156:157]
	v_pk_mul_f32 v[154:155], v[136:137], v[166:167]
	v_pk_mul_f32 v[168:169], v[134:135], v[168:169]
	v_pk_mul_f32 v[166:167], v[132:133], v[170:171]
	v_pk_mul_f32 v[172:173], v[130:131], v[172:173]
	v_pk_mul_f32 v[170:171], v[128:129], v[188:189]
	global_store_dwordx4 v[158:159], v[150:153], off nt
	global_store_dwordx4 v[158:159], v[154:157], off offset:64 nt
	global_store_dwordx4 v[158:159], v[166:169], off offset:512 nt
	global_store_dwordx4 v[158:159], v[170:173], off offset:576 nt
	v_mov_b32_e32 v150, v224
	v_mov_b32_e32 v151, v225
	v_mov_b32_e32 v152, v226
	v_mov_b32_e32 v153, v227
	s_nop 0
	v_mov_b32_e32 v154, v228
	v_mov_b32_e32 v155, v229
	v_mov_b32_e32 v156, v230
	v_mov_b32_e32 v157, v231
	v_mov_b32_e32 v158, v150
	v_mov_b32_e32 v159, v154
	v_mov_b32_e32 v154, v151
	v_mov_b32_e32 v150, v152
	v_mov_b32_e32 v151, v156
	v_mov_b32_e32 v156, v153
	v_pk_add_f32 v[152:153], v[158:159], v[154:155]
	v_pk_add_f32 v[150:151], v[150:151], v[156:157]
	v_lshl_add_u64 v[158:159], v[148:149], 0, v[176:177]
	v_pk_add_f32 v[150:151], v[152:153], v[150:151]
	s_nop 0
	v_add_f32_e32 v150, v150, v151
	ds_bpermute_b32 v151, v185, v150
	s_waitcnt lgkmcnt(0)
	v_add_f32_e32 v150, v150, v151
	ds_bpermute_b32 v151, v186, v150
	s_waitcnt lgkmcnt(0)
	v_add_f32_e32 v150, v150, v151
	v_fmamk_f32 v150, v150, 0x3a000000, v184
	v_rsq_f32_e32 v150, v150
	s_nop 0
	v_pk_mul_f32 v[154:155], v[52:53], v[150:151] op_sel_hi:[1,0]
	v_pk_mul_f32 v[152:153], v[54:55], v[150:151] op_sel_hi:[1,0]
	v_pk_mul_f32 v[166:167], v[48:49], v[150:151] op_sel_hi:[1,0]
	v_pk_mul_f32 v[156:157], v[50:51], v[150:151] op_sel_hi:[1,0]
	v_pk_mul_f32 v[170:171], v[20:21], v[150:151] op_sel_hi:[1,0]
	v_pk_mul_f32 v[168:169], v[22:23], v[150:151] op_sel_hi:[1,0]
	v_pk_mul_f32 v[174:175], v[16:17], v[150:151] op_sel_hi:[1,0]
	v_pk_mul_f32 v[172:173], v[18:19], v[150:151] op_sel_hi:[1,0]
	v_pk_mul_f32 v[152:153], v[142:143], v[152:153]
	v_pk_mul_f32 v[150:151], v[140:141], v[154:155]
	v_pk_mul_f32 v[156:157], v[138:139], v[156:157]
	v_pk_mul_f32 v[154:155], v[136:137], v[166:167]
	v_pk_mul_f32 v[168:169], v[134:135], v[168:169]
	v_pk_mul_f32 v[166:167], v[132:133], v[170:171]
	v_pk_mul_f32 v[172:173], v[130:131], v[172:173]
	v_pk_mul_f32 v[170:171], v[128:129], v[174:175]
	global_store_dwordx4 v[160:161], v[150:153], off nt
	global_store_dwordx4 v[160:161], v[154:157], off offset:64 nt
	global_store_dwordx4 v[160:161], v[166:169], off offset:512 nt
	global_store_dwordx4 v[160:161], v[170:173], off offset:576 nt
	v_mov_b32_e32 v150, v236
	v_mov_b32_e32 v151, v237
	v_mov_b32_e32 v152, v238
	v_mov_b32_e32 v153, v239
	s_nop 0
	v_mov_b32_e32 v154, v240
	v_mov_b32_e32 v155, v241
	v_mov_b32_e32 v156, v242
	v_mov_b32_e32 v157, v243
	v_lshl_add_u64 v[170:171], v[148:149], 0, v[178:179]
	v_mov_b32_e32 v158, v150
	v_mov_b32_e32 v159, v154
	v_mov_b32_e32 v154, v151
	v_mov_b32_e32 v150, v152
	v_mov_b32_e32 v151, v156
	v_mov_b32_e32 v156, v153
	v_pk_add_f32 v[152:153], v[158:159], v[154:155]
	v_pk_add_f32 v[150:151], v[150:151], v[156:157]
	s_nop 0
	v_pk_add_f32 v[150:151], v[152:153], v[150:151]
	s_nop 0
	v_add_f32_e32 v150, v150, v151
	ds_bpermute_b32 v151, v185, v150
	s_waitcnt lgkmcnt(0)
;     __device__ __forceinline__ void operator()(f32x4 (&acc)[2][2][4][2], const pg8::Unit& u, int wr, int wc, int fr, int fq) const {
;     ...
; #pragma unroll
;         for (int ai = 0; ai < 2; ++ai)
; #pragma unroll
;             for (int m = 0; m < 4; ++m) {
;                 const int row = row0 + ai * 128 + m * 16;
;                 const f32x4 pa = *(const f32x4*)(ss + (size_t)row * 32 + 8 * fq), pb = *(const f32x4*)(ss + (size_t)row * 32 + 8 * fq + 4);
;                 float sq = ((pa[0] + pa[1]) + (pa[2] + pa[3])) + ((pb[0] + pb[1]) + (pb[2] + pb[3]));
;                 sq += __shfl_xor(sq, 16); sq += __shfl_xor(sq, 32);
;                 const float rinv = __builtin_amdgcn_rsqf(sq * (1.0f / DM) + 1e-6f);
;                 float* orow = oy + (size_t)row * DM + col0;
; #pragma unroll
;                 for (int bj = 0; bj < 2; ++bj)
; #pragma unroll
;                     for (int n = 0; n < 2; ++n) __builtin_nontemporal_store(acc[ai][bj][m][n] * rinv * gg[bj][n], (f32x4*)(orow + bj * 128 + n * 16));
;             }
	v_add_f32_e32 v150, v150, v151
	ds_bpermute_b32 v151, v186, v150
	s_waitcnt lgkmcnt(0)
	v_add_f32_e32 v150, v150, v151
	v_fmamk_f32 v150, v150, 0x3a000000, v184
	v_rsq_f32_e32 v150, v150
	s_nop 0
	v_pk_mul_f32 v[154:155], v[44:45], v[150:151] op_sel_hi:[1,0]
	v_pk_mul_f32 v[152:153], v[46:47], v[150:151] op_sel_hi:[1,0]
	v_pk_mul_f32 v[158:159], v[40:41], v[150:151] op_sel_hi:[1,0]
	v_pk_mul_f32 v[156:157], v[42:43], v[150:151] op_sel_hi:[1,0]
	v_pk_mul_f32 v[166:167], v[12:13], v[150:151] op_sel_hi:[1,0]
	v_pk_mul_f32 v[160:161], v[14:15], v[150:151] op_sel_hi:[1,0]
	v_pk_mul_f32 v[172:173], v[8:9], v[150:151] op_sel_hi:[1,0]
	v_pk_mul_f32 v[168:169], v[10:11], v[150:151] op_sel_hi:[1,0]
	v_pk_mul_f32 v[152:153], v[142:143], v[152:153]
	v_pk_mul_f32 v[150:151], v[140:141], v[154:155]
	v_pk_mul_f32 v[156:157], v[138:139], v[156:157]
	v_pk_mul_f32 v[154:155], v[136:137], v[158:159]
	v_pk_mul_f32 v[160:161], v[134:135], v[160:161]
	v_pk_mul_f32 v[158:159], v[132:133], v[166:167]
	v_pk_mul_f32 v[168:169], v[130:131], v[168:169]
	v_pk_mul_f32 v[166:167], v[128:129], v[172:173]
	global_store_dwordx4 v[162:163], v[150:153], off nt
	global_store_dwordx4 v[162:163], v[154:157], off offset:64 nt
	global_store_dwordx4 v[162:163], v[158:161], off offset:512 nt
	global_store_dwordx4 v[162:163], v[166:169], off offset:576 nt
	v_mov_b32_e32 v150, v244
	v_mov_b32_e32 v151, v245
	v_mov_b32_e32 v152, v246
	v_mov_b32_e32 v153, v247
	s_nop 0
	v_mov_b32_e32 v154, v248
	v_mov_b32_e32 v155, v249
	v_mov_b32_e32 v156, v250
	v_mov_b32_e32 v157, v251
	v_mov_b32_e32 v158, v150
	v_mov_b32_e32 v159, v154
	v_mov_b32_e32 v154, v151
	v_mov_b32_e32 v150, v152
	v_mov_b32_e32 v151, v156
	v_mov_b32_e32 v156, v153
	v_pk_add_f32 v[152:153], v[158:159], v[154:155]
	v_pk_add_f32 v[150:151], v[150:151], v[156:157]
	s_nop 0
	v_pk_add_f32 v[150:151], v[152:153], v[150:151]
	s_nop 0
	v_add_f32_e32 v150, v150, v151
	ds_bpermute_b32 v151, v185, v150
	s_waitcnt lgkmcnt(0)
	v_add_f32_e32 v150, v150, v151
	ds_bpermute_b32 v151, v186, v150
	s_waitcnt lgkmcnt(0)
	v_add_f32_e32 v150, v150, v151
	v_fmamk_f32 v150, v150, 0x3a000000, v184
	v_rsq_f32_e32 v150, v150
	s_nop 0
	v_pk_mul_f32 v[152:153], v[36:37], v[150:151] op_sel_hi:[1,0]
	v_pk_mul_f32 v[154:155], v[38:39], v[150:151] op_sel_hi:[1,0]
	v_pk_mul_f32 v[156:157], v[32:33], v[150:151] op_sel_hi:[1,0]
	v_pk_mul_f32 v[158:159], v[34:35], v[150:151] op_sel_hi:[1,0]
	v_pk_mul_f32 v[160:161], v[4:5], v[150:151] op_sel_hi:[1,0]
	v_pk_mul_f32 v[162:163], v[6:7], v[150:151] op_sel_hi:[1,0]
	v_pk_mul_f32 v[166:167], v[0:1], v[150:151] op_sel_hi:[1,0]
	v_pk_mul_f32 v[150:151], v[2:3], v[150:151] op_sel_hi:[1,0]
	v_pk_mul_f32 v[142:143], v[142:143], v[154:155]
	v_pk_mul_f32 v[140:141], v[140:141], v[152:153]
	v_pk_mul_f32 v[138:139], v[138:139], v[158:159]
	v_pk_mul_f32 v[136:137], v[136:137], v[156:157]
	v_pk_mul_f32 v[134:135], v[134:135], v[162:163]
	v_pk_mul_f32 v[132:133], v[132:133], v[160:161]
	v_pk_mul_f32 v[130:131], v[130:131], v[150:151]
	v_pk_mul_f32 v[128:129], v[128:129], v[166:167]
	global_store_dwordx4 v[164:165], v[140:143], off nt
	global_store_dwordx4 v[164:165], v[136:139], off offset:64 nt
	global_store_dwordx4 v[164:165], v[132:135], off offset:512 nt
	global_store_dwordx4 v[164:165], v[128:131], off offset:576 nt
	s_cbranch_vccnz .LBB0_848
	s_andn2_b64 vcc, exec, s[18:19]
	s_cbranch_vccnz .LBB0_847
	s_barrier
	s_branch .LBB0_847
